# acc zeroing via v_mov_b64 (64 instead of 128 movs per tile)
# baseline (speedup 1.0000x reference)
;     __device__ __forceinline__ bool next(int i, pg8::Unit& u) const { if (!base.next(i >> 2, u)) return false; u.sub = i & 3; return true; }
; template <class Epi, class Sched, bool ALIGN_EPI = false, bool SP2 = false>
; __device__ __forceinline__ void gemm_phase(PG8_LAS unsigned char* lds, const Gemm g, const Sched& S, const Epi& E, const int tid) {
;     ...
;         const bool has_next = S.next(ui + 1, nxt);
;         const char* nA = has_next ? S.aptr(nxt) : cA; const char* nB = has_next ? S.bptr(nxt) : cB;
;     ...
; #pragma unroll
;         for (int a = 0; a < 2; ++a)
; #pragma unroll
;             for (int b = 0; b < 2; ++b)
; #pragma unroll
;                 for (int m = 0; m < 4; ++m)
; #pragma unroll
;                     for (int n = 0; n < 2; ++n) acc[a][b][m][n] = (f32x4){0.f, 0.f, 0.f, 0.f};
.LBB0_338:
	s_ashr_i32 s29, s28, 31
	s_lshl_b64 s[18:19], s[28:29], 19
	s_add_u32 s30, s46, s18
	s_addc_u32 s31, s47, s19
	s_and_b64 s[18:19], s[2:3], exec
	s_cselect_b32 s29, s31, s41
	s_cselect_b32 s62, s30, s40
	s_ashr_i32 s27, s26, 31
	s_lshl_b64 s[18:19], s[26:27], 19
	s_add_u32 s34, s48, s18
	s_addc_u32 s35, s49, s19
	s_and_b64 s[18:19], s[2:3], exec
	s_cselect_b32 s27, s35, s39
	s_cselect_b32 s63, s34, s38
	s_add_u32 s64, s38, 0x100
	s_addc_u32 s65, s39, 0
	s_add_u32 s38, s40, 0x40080
	v_mov_b64_e32 v[2:3], 0
	s_addc_u32 s39, s41, 0
	s_mov_b32 s66, -2
	v_mov_b64_e32 v[4:5], 0
	v_mov_b64_e32 v[6:7], 0
	v_mov_b64_e32 v[8:9], 0
	v_mov_b64_e32 v[10:11], 0
	v_mov_b64_e32 v[12:13], 0
	v_mov_b64_e32 v[14:15], 0
	v_mov_b64_e32 v[16:17], 0
	v_mov_b64_e32 v[18:19], 0
	v_mov_b64_e32 v[20:21], 0
	v_mov_b64_e32 v[22:23], 0
	v_mov_b64_e32 v[24:25], 0
	v_mov_b64_e32 v[26:27], 0
	v_mov_b64_e32 v[28:29], 0
	v_mov_b64_e32 v[30:31], 0
	v_mov_b64_e32 v[32:33], 0
	v_mov_b64_e32 v[34:35], 0
	v_mov_b64_e32 v[36:37], 0
	v_mov_b64_e32 v[38:39], 0
	v_mov_b64_e32 v[40:41], 0
	v_mov_b64_e32 v[42:43], 0
	v_mov_b64_e32 v[44:45], 0
	v_mov_b64_e32 v[46:47], 0
	v_mov_b64_e32 v[48:49], 0
	v_mov_b64_e32 v[50:51], 0
	v_mov_b64_e32 v[52:53], 0
	v_mov_b64_e32 v[54:55], 0
	v_mov_b64_e32 v[56:57], 0
	v_mov_b64_e32 v[58:59], 0
	v_mov_b64_e32 v[60:61], 0
	v_mov_b64_e32 v[62:63], 0
	v_mov_b64_e32 v[64:65], 0
	v_mov_b64_e32 v[66:67], 0
	v_mov_b64_e32 v[68:69], 0
	v_mov_b64_e32 v[70:71], 0
	v_mov_b64_e32 v[72:73], 0
	v_mov_b64_e32 v[74:75], 0
	v_mov_b64_e32 v[76:77], 0
	v_mov_b64_e32 v[78:79], 0
	v_mov_b64_e32 v[80:81], 0
	v_mov_b64_e32 v[82:83], 0
	v_mov_b64_e32 v[84:85], 0
	v_mov_b64_e32 v[86:87], 0
	v_mov_b64_e32 v[88:89], 0
	v_mov_b64_e32 v[90:91], 0
	v_mov_b64_e32 v[92:93], 0
	v_mov_b64_e32 v[94:95], 0
	v_mov_b64_e32 v[96:97], 0
	v_mov_b64_e32 v[98:99], 0
	v_mov_b64_e32 v[100:101], 0
	v_mov_b64_e32 v[102:103], 0
	v_mov_b64_e32 v[104:105], 0
	v_mov_b64_e32 v[106:107], 0
	v_mov_b64_e32 v[108:109], 0
	v_mov_b64_e32 v[110:111], 0
	v_mov_b64_e32 v[112:113], 0
	v_mov_b64_e32 v[114:115], 0
	v_mov_b64_e32 v[116:117], 0
	v_mov_b64_e32 v[118:119], 0
	v_mov_b64_e32 v[120:121], 0
	v_mov_b64_e32 v[122:123], 0
	v_mov_b64_e32 v[124:125], 0
	v_mov_b64_e32 v[126:127], 0
	v_mov_b64_e32 v[128:129], 0

; template <class Epi, class Sched, bool ALIGN_EPI = false, bool SP2 = false>
; __device__ __forceinline__ void gemm_phase(PG8_LAS unsigned char* lds, const Gemm g, const Sched& S, const Epi& E, const int tid) {
;     ...
; #pragma unroll
;         for (int a = 0; a < 2; ++a)
; #pragma unroll
;             for (int b = 0; b < 2; ++b)
; #pragma unroll
;                 for (int m = 0; m < 4; ++m)
; #pragma unroll
;                     for (int n = 0; n < 2; ++n) acc[a][b][m][n] = (f32x4){0.f, 0.f, 0.f, 0.f};
.LBB0_422:
	s_add_u32 s45, s8, 0x100
	v_mov_b64_e32 v[2:3], 0
	s_addc_u32 s47, s9, 0
	s_mov_b32 s77, -2
	v_mov_b64_e32 v[4:5], 0
	v_mov_b64_e32 v[6:7], 0
	v_mov_b64_e32 v[8:9], 0
	v_mov_b64_e32 v[10:11], 0
	v_mov_b64_e32 v[12:13], 0
	v_mov_b64_e32 v[14:15], 0
	v_mov_b64_e32 v[16:17], 0
	v_mov_b64_e32 v[18:19], 0
	v_mov_b64_e32 v[20:21], 0
	v_mov_b64_e32 v[22:23], 0
	v_mov_b64_e32 v[24:25], 0
	v_mov_b64_e32 v[26:27], 0
	v_mov_b64_e32 v[28:29], 0
	v_mov_b64_e32 v[30:31], 0
	v_mov_b64_e32 v[32:33], 0
	v_mov_b64_e32 v[34:35], 0
	v_mov_b64_e32 v[36:37], 0
	v_mov_b64_e32 v[38:39], 0
	v_mov_b64_e32 v[40:41], 0
	v_mov_b64_e32 v[42:43], 0
	v_mov_b64_e32 v[44:45], 0
	v_mov_b64_e32 v[46:47], 0
	v_mov_b64_e32 v[48:49], 0
	v_mov_b64_e32 v[50:51], 0
	v_mov_b64_e32 v[52:53], 0
	v_mov_b64_e32 v[54:55], 0
	v_mov_b64_e32 v[56:57], 0
	v_mov_b64_e32 v[58:59], 0
	v_mov_b64_e32 v[60:61], 0
	v_mov_b64_e32 v[62:63], 0
	v_mov_b64_e32 v[64:65], 0
	v_mov_b64_e32 v[66:67], 0
	v_mov_b64_e32 v[68:69], 0
	v_mov_b64_e32 v[70:71], 0
	v_mov_b64_e32 v[72:73], 0
	v_mov_b64_e32 v[74:75], 0
	v_mov_b64_e32 v[76:77], 0
	v_mov_b64_e32 v[78:79], 0
	v_mov_b64_e32 v[80:81], 0
	v_mov_b64_e32 v[82:83], 0
	v_mov_b64_e32 v[84:85], 0
	v_mov_b64_e32 v[86:87], 0
	v_mov_b64_e32 v[88:89], 0
	v_mov_b64_e32 v[90:91], 0
	v_mov_b64_e32 v[92:93], 0
	v_mov_b64_e32 v[94:95], 0
	v_mov_b64_e32 v[96:97], 0
	v_mov_b64_e32 v[98:99], 0
	v_mov_b64_e32 v[100:101], 0
	v_mov_b64_e32 v[102:103], 0
	v_mov_b64_e32 v[104:105], 0
	v_mov_b64_e32 v[106:107], 0
	v_mov_b64_e32 v[108:109], 0
	v_mov_b64_e32 v[110:111], 0
	v_mov_b64_e32 v[112:113], 0
	v_mov_b64_e32 v[114:115], 0
	v_mov_b64_e32 v[116:117], 0
	v_mov_b64_e32 v[118:119], 0
	v_mov_b64_e32 v[120:121], 0
	v_mov_b64_e32 v[122:123], 0
	v_mov_b64_e32 v[124:125], 0
	v_mov_b64_e32 v[126:127], 0
	v_mov_b64_e32 v[128:129], 0

;     __device__ __forceinline__ bool next(int i, pg8::Unit& u) const { if (!base.next(i >> 2, u)) return false; u.sub = i & 3; return true; }
; template <class Epi, class Sched, bool ALIGN_EPI = false, bool SP2 = false>
; __device__ __forceinline__ void gemm_phase(PG8_LAS unsigned char* lds, const Gemm g, const Sched& S, const Epi& E, const int tid) {
;     ...
;         const bool has_next = S.next(ui + 1, nxt);
;         const char* nA = has_next ? S.aptr(nxt) : cA; const char* nB = has_next ? S.bptr(nxt) : cB;
;     ...
; #pragma unroll
;         for (int a = 0; a < 2; ++a)
; #pragma unroll
;             for (int b = 0; b < 2; ++b)
; #pragma unroll
;                 for (int m = 0; m < 4; ++m)
; #pragma unroll
;                     for (int n = 0; n < 2; ++n) acc[a][b][m][n] = (f32x4){0.f, 0.f, 0.f, 0.f};
.LBB0_732:
	s_ashr_i32 s29, s28, 31
	s_lshl_b64 s[18:19], s[28:29], 19
	s_add_u32 s30, s50, s18
	s_addc_u32 s31, s51, s19
	s_and_b64 s[18:19], s[2:3], exec
	s_cselect_b32 s29, s31, s41
	s_cselect_b32 s37, s30, s40
	s_ashr_i32 s27, s26, 31
	s_lshl_b64 s[18:19], s[26:27], 19
	s_add_u32 s34, s52, s18
	s_addc_u32 s35, s53, s19
	s_and_b64 s[18:19], s[2:3], exec
	s_cselect_b32 s27, s35, s39
	s_cselect_b32 s79, s34, s38
	s_add_u32 s80, s38, 0x100
	s_addc_u32 s81, s39, 0
	s_add_u32 s38, s40, 0x40080
	v_mov_b64_e32 v[2:3], 0
	s_addc_u32 s39, s41, 0
	s_mov_b32 s82, -2
	v_mov_b64_e32 v[4:5], 0
	v_mov_b64_e32 v[6:7], 0
	v_mov_b64_e32 v[8:9], 0
	v_mov_b64_e32 v[10:11], 0
	v_mov_b64_e32 v[12:13], 0
	v_mov_b64_e32 v[14:15], 0
	v_mov_b64_e32 v[16:17], 0
	v_mov_b64_e32 v[18:19], 0
	v_mov_b64_e32 v[20:21], 0
	v_mov_b64_e32 v[22:23], 0
	v_mov_b64_e32 v[24:25], 0
	v_mov_b64_e32 v[26:27], 0
	v_mov_b64_e32 v[28:29], 0
	v_mov_b64_e32 v[30:31], 0
	v_mov_b64_e32 v[32:33], 0
	v_mov_b64_e32 v[34:35], 0
	v_mov_b64_e32 v[36:37], 0
	v_mov_b64_e32 v[38:39], 0
	v_mov_b64_e32 v[40:41], 0
	v_mov_b64_e32 v[42:43], 0
	v_mov_b64_e32 v[44:45], 0
	v_mov_b64_e32 v[46:47], 0
	v_mov_b64_e32 v[48:49], 0
	v_mov_b64_e32 v[50:51], 0
	v_mov_b64_e32 v[52:53], 0
	v_mov_b64_e32 v[54:55], 0
	v_mov_b64_e32 v[56:57], 0
	v_mov_b64_e32 v[58:59], 0
	v_mov_b64_e32 v[60:61], 0
	v_mov_b64_e32 v[62:63], 0
	v_mov_b64_e32 v[64:65], 0
	v_mov_b64_e32 v[66:67], 0
	v_mov_b64_e32 v[68:69], 0
	v_mov_b64_e32 v[70:71], 0
	v_mov_b64_e32 v[72:73], 0
	v_mov_b64_e32 v[74:75], 0
	v_mov_b64_e32 v[76:77], 0
	v_mov_b64_e32 v[78:79], 0
	v_mov_b64_e32 v[80:81], 0
	v_mov_b64_e32 v[82:83], 0
	v_mov_b64_e32 v[84:85], 0
	v_mov_b64_e32 v[86:87], 0
	v_mov_b64_e32 v[88:89], 0
	v_mov_b64_e32 v[90:91], 0
	v_mov_b64_e32 v[92:93], 0
	v_mov_b64_e32 v[94:95], 0
	v_mov_b64_e32 v[96:97], 0
	v_mov_b64_e32 v[98:99], 0
	v_mov_b64_e32 v[100:101], 0
	v_mov_b64_e32 v[102:103], 0
	v_mov_b64_e32 v[104:105], 0
	v_mov_b64_e32 v[106:107], 0
	v_mov_b64_e32 v[108:109], 0
	v_mov_b64_e32 v[110:111], 0
	v_mov_b64_e32 v[112:113], 0
	v_mov_b64_e32 v[114:115], 0
	v_mov_b64_e32 v[116:117], 0
	v_mov_b64_e32 v[118:119], 0
	v_mov_b64_e32 v[120:121], 0
	v_mov_b64_e32 v[122:123], 0
	v_mov_b64_e32 v[124:125], 0
	v_mov_b64_e32 v[126:127], 0
	v_mov_b64_e32 v[128:129], 0

; template <class Epi, class Sched, bool ALIGN_EPI = false, bool SP2 = false>
; __device__ __forceinline__ void gemm_phase(PG8_LAS unsigned char* lds, const Gemm g, const Sched& S, const Epi& E, const int tid) {
;     ...
; #pragma unroll
;         for (int a = 0; a < 2; ++a)
; #pragma unroll
;             for (int b = 0; b < 2; ++b)
; #pragma unroll
;                 for (int m = 0; m < 4; ++m)
; #pragma unroll
;                     for (int n = 0; n < 2; ++n) acc[a][b][m][n] = (f32x4){0.f, 0.f, 0.f, 0.f};
.LBB0_1121:
	s_add_u32 s5, s56, 0x100
	s_addc_u32 s49, s57, 0
	s_add_u32 s56, s58, 0x40080
	v_mov_b64_e32 v[2:3], 0
	s_addc_u32 s57, s59, 0
	s_mov_b32 s51, -2
	v_mov_b64_e32 v[4:5], 0
	v_mov_b64_e32 v[6:7], 0
	v_mov_b64_e32 v[8:9], 0
	v_mov_b64_e32 v[10:11], 0
	v_mov_b64_e32 v[12:13], 0
	v_mov_b64_e32 v[14:15], 0
	v_mov_b64_e32 v[16:17], 0
	v_mov_b64_e32 v[18:19], 0
	v_mov_b64_e32 v[20:21], 0
	v_mov_b64_e32 v[22:23], 0
	v_mov_b64_e32 v[24:25], 0
	v_mov_b64_e32 v[26:27], 0
	v_mov_b64_e32 v[28:29], 0
	v_mov_b64_e32 v[30:31], 0
	v_mov_b64_e32 v[32:33], 0
	v_mov_b64_e32 v[34:35], 0
	v_mov_b64_e32 v[36:37], 0
	v_mov_b64_e32 v[38:39], 0
	v_mov_b64_e32 v[40:41], 0
	v_mov_b64_e32 v[42:43], 0
	v_mov_b64_e32 v[44:45], 0
	v_mov_b64_e32 v[46:47], 0
	v_mov_b64_e32 v[48:49], 0
	v_mov_b64_e32 v[50:51], 0
	v_mov_b64_e32 v[52:53], 0
	v_mov_b64_e32 v[54:55], 0
	v_mov_b64_e32 v[56:57], 0
	v_mov_b64_e32 v[58:59], 0
	v_mov_b64_e32 v[60:61], 0
	v_mov_b64_e32 v[62:63], 0
	v_mov_b64_e32 v[64:65], 0
	v_mov_b64_e32 v[66:67], 0
	v_mov_b64_e32 v[68:69], 0
	v_mov_b64_e32 v[70:71], 0
	v_mov_b64_e32 v[72:73], 0
	v_mov_b64_e32 v[74:75], 0
	v_mov_b64_e32 v[76:77], 0
	v_mov_b64_e32 v[78:79], 0
	v_mov_b64_e32 v[80:81], 0
	v_mov_b64_e32 v[82:83], 0
	v_mov_b64_e32 v[84:85], 0
	v_mov_b64_e32 v[86:87], 0
	v_mov_b64_e32 v[88:89], 0
	v_mov_b64_e32 v[90:91], 0
	v_mov_b64_e32 v[92:93], 0
	v_mov_b64_e32 v[94:95], 0
	v_mov_b64_e32 v[96:97], 0
	v_mov_b64_e32 v[98:99], 0
	v_mov_b64_e32 v[100:101], 0
	v_mov_b64_e32 v[102:103], 0
	v_mov_b64_e32 v[104:105], 0
	v_mov_b64_e32 v[106:107], 0
	v_mov_b64_e32 v[108:109], 0
	v_mov_b64_e32 v[110:111], 0
	v_mov_b64_e32 v[112:113], 0
	v_mov_b64_e32 v[114:115], 0
	v_mov_b64_e32 v[116:117], 0
	v_mov_b64_e32 v[118:119], 0
	v_mov_b64_e32 v[120:121], 0
	v_mov_b64_e32 v[122:123], 0
	v_mov_b64_e32 v[124:125], 0
	v_mov_b64_e32 v[126:127], 0
	v_mov_b64_e32 v[128:129], 0

;     __device__ __forceinline__ bool next(int i, pg8::Unit& u) const { if (!base.next(i >> 2, u)) return false; u.sub = i & 3; return true; }
; template <class Epi, class Sched, bool ALIGN_EPI = false, bool SP2 = false>
; __device__ __forceinline__ void gemm_phase(PG8_LAS unsigned char* lds, const Gemm g, const Sched& S, const Epi& E, const int tid) {
;     ...
;         const bool has_next = S.next(ui + 1, nxt);
;         const char* nA = has_next ? S.aptr(nxt) : cA; const char* nB = has_next ? S.bptr(nxt) : cB;
;     ...
; #pragma unroll
;         for (int a = 0; a < 2; ++a)
; #pragma unroll
;             for (int b = 0; b < 2; ++b)
; #pragma unroll
;                 for (int m = 0; m < 4; ++m)
; #pragma unroll
;                     for (int n = 0; n < 2; ++n) acc[a][b][m][n] = (f32x4){0.f, 0.f, 0.f, 0.f};
.LBB0_1373:
	s_ashr_i32 s39, s38, 31
	s_lshl_b64 s[18:19], s[38:39], 19
	s_add_u32 s40, s52, s18
	s_addc_u32 s41, s53, s19
	s_and_b64 s[18:19], s[4:5], exec
	s_cselect_b32 s7, s41, s11
	s_cselect_b32 s39, s40, s10
	s_ashr_i32 s37, s36, 31
	s_lshl_b64 s[18:19], s[36:37], 19
	s_add_u32 s42, s54, s18
	s_addc_u32 s43, s55, s19
	s_and_b64 s[18:19], s[4:5], exec
	s_cselect_b32 s37, s43, s9
	s_cselect_b32 s45, s42, s8
	s_add_u32 s48, s8, 0x100
	s_addc_u32 s49, s9, 0
	s_add_u32 s8, s10, 0x40080
	v_mov_b64_e32 v[2:3], 0
	s_addc_u32 s9, s11, 0
	s_mov_b32 s76, -2
	v_mov_b64_e32 v[4:5], 0
	v_mov_b64_e32 v[6:7], 0
	v_mov_b64_e32 v[8:9], 0
	v_mov_b64_e32 v[10:11], 0
	v_mov_b64_e32 v[12:13], 0
	v_mov_b64_e32 v[14:15], 0
	v_mov_b64_e32 v[16:17], 0
	v_mov_b64_e32 v[18:19], 0
	v_mov_b64_e32 v[20:21], 0
	v_mov_b64_e32 v[22:23], 0
	v_mov_b64_e32 v[24:25], 0
	v_mov_b64_e32 v[26:27], 0
	v_mov_b64_e32 v[28:29], 0
	v_mov_b64_e32 v[30:31], 0
	v_mov_b64_e32 v[32:33], 0
	v_mov_b64_e32 v[34:35], 0
	v_mov_b64_e32 v[36:37], 0
	v_mov_b64_e32 v[38:39], 0
	v_mov_b64_e32 v[40:41], 0
	v_mov_b64_e32 v[42:43], 0
	v_mov_b64_e32 v[44:45], 0
	v_mov_b64_e32 v[46:47], 0
	v_mov_b64_e32 v[48:49], 0
	v_mov_b64_e32 v[50:51], 0
	v_mov_b64_e32 v[52:53], 0
	v_mov_b64_e32 v[54:55], 0
	v_mov_b64_e32 v[56:57], 0
	v_mov_b64_e32 v[58:59], 0
	v_mov_b64_e32 v[60:61], 0
	v_mov_b64_e32 v[62:63], 0
	v_mov_b64_e32 v[64:65], 0
	v_mov_b64_e32 v[66:67], 0
	v_mov_b64_e32 v[68:69], 0
	v_mov_b64_e32 v[70:71], 0
	v_mov_b64_e32 v[72:73], 0
	v_mov_b64_e32 v[74:75], 0
	v_mov_b64_e32 v[76:77], 0
	v_mov_b64_e32 v[78:79], 0
	v_mov_b64_e32 v[80:81], 0
	v_mov_b64_e32 v[82:83], 0
	v_mov_b64_e32 v[84:85], 0
	v_mov_b64_e32 v[86:87], 0
	v_mov_b64_e32 v[88:89], 0
	v_mov_b64_e32 v[90:91], 0
	v_mov_b64_e32 v[92:93], 0
	v_mov_b64_e32 v[94:95], 0
	v_mov_b64_e32 v[96:97], 0
	v_mov_b64_e32 v[98:99], 0
	v_mov_b64_e32 v[100:101], 0
	v_mov_b64_e32 v[102:103], 0
	v_mov_b64_e32 v[104:105], 0
	v_mov_b64_e32 v[106:107], 0
	v_mov_b64_e32 v[108:109], 0
	v_mov_b64_e32 v[110:111], 0
	v_mov_b64_e32 v[112:113], 0
	v_mov_b64_e32 v[114:115], 0
	v_mov_b64_e32 v[116:117], 0
	v_mov_b64_e32 v[118:119], 0
	v_mov_b64_e32 v[120:121], 0
	v_mov_b64_e32 v[122:123], 0
	v_mov_b64_e32 v[124:125], 0
	v_mov_b64_e32 v[126:127], 0
	v_mov_b64_e32 v[128:129], 0

; template <class Epi, class Sched, bool ALIGN_EPI = false, bool SP2 = false>
; __device__ __forceinline__ void gemm_phase(PG8_LAS unsigned char* lds, const Gemm g, const Sched& S, const Epi& E, const int tid) {
;     ...
; #pragma unroll
;         for (int a = 0; a < 2; ++a)
; #pragma unroll
;             for (int b = 0; b < 2; ++b)
; #pragma unroll
;                 for (int m = 0; m < 4; ++m)
; #pragma unroll
;                     for (int n = 0; n < 2; ++n) acc[a][b][m][n] = (f32x4){0.f, 0.f, 0.f, 0.f};
.LBB0_5219:
	s_add_u32 s43, s8, 0x100
	v_mov_b64_e32 v[2:3], 0
	s_addc_u32 s45, s9, 0
	s_mov_b32 s74, -2
	v_mov_b64_e32 v[4:5], 0
	v_mov_b64_e32 v[6:7], 0
	v_mov_b64_e32 v[8:9], 0
	v_mov_b64_e32 v[10:11], 0
	v_mov_b64_e32 v[12:13], 0
	v_mov_b64_e32 v[14:15], 0
	v_mov_b64_e32 v[16:17], 0
	v_mov_b64_e32 v[18:19], 0
	v_mov_b64_e32 v[20:21], 0
	v_mov_b64_e32 v[22:23], 0
	v_mov_b64_e32 v[24:25], 0
	v_mov_b64_e32 v[26:27], 0
	v_mov_b64_e32 v[28:29], 0
	v_mov_b64_e32 v[30:31], 0
	v_mov_b64_e32 v[32:33], 0
	v_mov_b64_e32 v[34:35], 0
	v_mov_b64_e32 v[36:37], 0
	v_mov_b64_e32 v[38:39], 0
	v_mov_b64_e32 v[40:41], 0
	v_mov_b64_e32 v[42:43], 0
	v_mov_b64_e32 v[44:45], 0
	v_mov_b64_e32 v[46:47], 0
	v_mov_b64_e32 v[48:49], 0
	v_mov_b64_e32 v[50:51], 0
	v_mov_b64_e32 v[52:53], 0
	v_mov_b64_e32 v[54:55], 0
	v_mov_b64_e32 v[56:57], 0
	v_mov_b64_e32 v[58:59], 0
	v_mov_b64_e32 v[60:61], 0
	v_mov_b64_e32 v[62:63], 0
	v_mov_b64_e32 v[64:65], 0
	v_mov_b64_e32 v[66:67], 0
	v_mov_b64_e32 v[68:69], 0
	v_mov_b64_e32 v[70:71], 0
	v_mov_b64_e32 v[72:73], 0
	v_mov_b64_e32 v[74:75], 0
	v_mov_b64_e32 v[76:77], 0
	v_mov_b64_e32 v[78:79], 0
	v_mov_b64_e32 v[80:81], 0
	v_mov_b64_e32 v[82:83], 0
	v_mov_b64_e32 v[84:85], 0
	v_mov_b64_e32 v[86:87], 0
	v_mov_b64_e32 v[88:89], 0
	v_mov_b64_e32 v[90:91], 0
	v_mov_b64_e32 v[92:93], 0
	v_mov_b64_e32 v[94:95], 0
	v_mov_b64_e32 v[96:97], 0
	v_mov_b64_e32 v[98:99], 0
	v_mov_b64_e32 v[100:101], 0
	v_mov_b64_e32 v[102:103], 0
	v_mov_b64_e32 v[104:105], 0
	v_mov_b64_e32 v[106:107], 0
	v_mov_b64_e32 v[108:109], 0
	v_mov_b64_e32 v[110:111], 0
	v_mov_b64_e32 v[112:113], 0
	v_mov_b64_e32 v[114:115], 0
	v_mov_b64_e32 v[116:117], 0
	v_mov_b64_e32 v[118:119], 0
	v_mov_b64_e32 v[120:121], 0
	v_mov_b64_e32 v[122:123], 0
	v_mov_b64_e32 v[124:125], 0
	v_mov_b64_e32 v[126:127], 0
	v_mov_b64_e32 v[128:129], 0

; template <class Epi, class Sched, bool ALIGN_EPI = false, bool SP2 = false>
; __device__ __forceinline__ void gemm_phase(PG8_LAS unsigned char* lds, const Gemm g, const Sched& S, const Epi& E, const int tid) {
;     ...
; #pragma unroll
;         for (int a = 0; a < 2; ++a)
; #pragma unroll
;             for (int b = 0; b < 2; ++b)
; #pragma unroll
;                 for (int m = 0; m < 4; ++m)
; #pragma unroll
;                     for (int n = 0; n < 2; ++n) acc[a][b][m][n] = (f32x4){0.f, 0.f, 0.f, 0.f};
.LBB0_5776:
	s_add_u32 s5, s54, 0x100
	s_addc_u32 s47, s55, 0
	s_add_u32 s54, s56, 0x40080
	v_mov_b64_e32 v[2:3], 0
	s_addc_u32 s55, s57, 0
	s_mov_b32 s49, -2
	v_mov_b64_e32 v[4:5], 0
	v_mov_b64_e32 v[6:7], 0
	v_mov_b64_e32 v[8:9], 0
	v_mov_b64_e32 v[10:11], 0
	v_mov_b64_e32 v[12:13], 0
	v_mov_b64_e32 v[14:15], 0
	v_mov_b64_e32 v[16:17], 0
	v_mov_b64_e32 v[18:19], 0
	v_mov_b64_e32 v[20:21], 0
	v_mov_b64_e32 v[22:23], 0
	v_mov_b64_e32 v[24:25], 0
	v_mov_b64_e32 v[26:27], 0
	v_mov_b64_e32 v[28:29], 0
	v_mov_b64_e32 v[30:31], 0
	v_mov_b64_e32 v[32:33], 0
	v_mov_b64_e32 v[34:35], 0
	v_mov_b64_e32 v[36:37], 0
	v_mov_b64_e32 v[38:39], 0
	v_mov_b64_e32 v[40:41], 0
	v_mov_b64_e32 v[42:43], 0
	v_mov_b64_e32 v[44:45], 0
	v_mov_b64_e32 v[46:47], 0
	v_mov_b64_e32 v[48:49], 0
	v_mov_b64_e32 v[50:51], 0
	v_mov_b64_e32 v[52:53], 0
	v_mov_b64_e32 v[54:55], 0
	v_mov_b64_e32 v[56:57], 0
	v_mov_b64_e32 v[58:59], 0
	v_mov_b64_e32 v[60:61], 0
	v_mov_b64_e32 v[62:63], 0
	v_mov_b64_e32 v[64:65], 0
	v_mov_b64_e32 v[66:67], 0
	v_mov_b64_e32 v[68:69], 0
	v_mov_b64_e32 v[70:71], 0
	v_mov_b64_e32 v[72:73], 0
	v_mov_b64_e32 v[74:75], 0
	v_mov_b64_e32 v[76:77], 0
	v_mov_b64_e32 v[78:79], 0
	v_mov_b64_e32 v[80:81], 0
	v_mov_b64_e32 v[82:83], 0
	v_mov_b64_e32 v[84:85], 0
	v_mov_b64_e32 v[86:87], 0
	v_mov_b64_e32 v[88:89], 0
	v_mov_b64_e32 v[90:91], 0
	v_mov_b64_e32 v[92:93], 0
	v_mov_b64_e32 v[94:95], 0
	v_mov_b64_e32 v[96:97], 0
	v_mov_b64_e32 v[98:99], 0
	v_mov_b64_e32 v[100:101], 0
	v_mov_b64_e32 v[102:103], 0
	v_mov_b64_e32 v[104:105], 0
	v_mov_b64_e32 v[106:107], 0
	v_mov_b64_e32 v[108:109], 0
	v_mov_b64_e32 v[110:111], 0
	v_mov_b64_e32 v[112:113], 0
	v_mov_b64_e32 v[114:115], 0
	v_mov_b64_e32 v[116:117], 0
	v_mov_b64_e32 v[118:119], 0
	v_mov_b64_e32 v[120:121], 0
	v_mov_b64_e32 v[122:123], 0
	v_mov_b64_e32 v[124:125], 0
	v_mov_b64_e32 v[126:127], 0
	v_mov_b64_e32 v[128:129], 0
